# one slack CU per XCD issues an un-waited L2 writeback right after the P1->GEMM1 seam so no P1-written h line can stay dirty until another XCD overwrites that address (Q image)
# baseline (speedup 1.0000x reference)
; #define SEAM(k) do { if (IN(k) && IN((k) + 1)) { xcd_barrier(bar); } } while (0)
;     __host__ __device__ bool next(int i, Unit& u) const {
;         const long L = (long)i * G + c; if (L >= nwg) return false;
;         int wgid = (int)L; { const int q = nwg / NXCD, r = nwg % NXCD, xcd = wgid % NXCD, off = wgid / NXCD; wgid = (xcd < r ? xcd * (q + 1) : r * (q + 1) + (xcd - r) * q) + off; }
;         const int nig = WGM * nN, gid = wgid / nig, fm = gid * WGM, gsz = (nM - fm) < WGM ? (nM - fm) : WGM;
;         u.pm = fm + ((wgid % nig) % gsz); u.pn = (wgid % nig) / gsz; return true;
;     }
; __global__ void __launch_bounds__(512, 2) fwd_kernel(Args a) {
;     ...
;     if (IN(1)) { phase1(P, G); } SEAM(1);
;     if (IN(2)) {
;         { pg8::Gemm g{(const bf16_t*)(P.ws + WS_H), (const bf16_t*)(P.ws + WS_WIN), T, 5888, DM}; pg8::StaticOrder S; S.init(T, 5888, G, bx);
;           EpiInProj E{P.ws, P.out};
;           pg8::gemm_phase<EpiInProj, pg8::StaticOrder, true, true>(lds, g, S, E); }
.LBB0_338:
	s_or_b64 exec, exec, s[2:3]
	s_waitcnt lgkmcnt(0)
	s_barrier
	s_cmp_lg_u32 s98, 0
	s_cbranch_scc1 .Lwb_skip
	s_lshr_b32 s99, s80, 3
	s_cmp_lg_u32 s99, 31
	s_cbranch_scc1 .Lwb_skip
	v_readlane_b32 s99, v254, 5
	s_cmp_eq_u32 s99, 0
	s_cbranch_scc1 .Lwb_skip
	buffer_wbl2 sc1
.Lwb_skip:
.LBB0_339:
	s_cmp_lt_i32 s92, 3
	s_cselect_b64 s[2:3], -1, 0
	s_and_b64 s[0:1], s[2:3], s[0:1]
	s_andn2_b64 vcc, exec, s[0:1]
	s_mov_b64 s[0:1], s[48:49]
	s_mov_b64 s[14:15], s[62:63]
	v_writelane_b32 v254, s0, 23
	s_nop 1
	v_writelane_b32 v254, s1, 24
	v_writelane_b32 v254, s2, 25
	v_writelane_b32 v254, s3, 26
	v_writelane_b32 v254, s4, 27
	v_writelane_b32 v254, s5, 28
	v_writelane_b32 v254, s6, 29
	v_writelane_b32 v254, s7, 30
	v_writelane_b32 v254, s8, 31
	v_writelane_b32 v254, s9, 32
	v_writelane_b32 v254, s10, 33
	v_writelane_b32 v254, s11, 34
	v_writelane_b32 v254, s12, 35
	v_writelane_b32 v254, s13, 36
	v_writelane_b32 v254, s14, 37
	v_writelane_b32 v254, s15, 38
	s_cbranch_vccnz .LBB0_1057
	s_cmpk_lt_i32 s80, 0xb80
	v_readfirstlane_b32 s11, v200
	s_movk_i32 s0, 0x400
	s_cselect_b64 s[2:3], -1, 0
	s_cmpk_gt_i32 s80, 0xb7f
	s_cbranch_scc1 .LBB0_342
	s_ashr_i32 s1, s80, 31
	s_lshr_b32 s1, s1, 29
	s_add_i32 s1, s80, s1
	s_ashr_i32 s4, s1, 3
	s_and_b32 s1, s1, -8
	s_sub_i32 s1, s80, s1
	s_cmp_lt_i32 s1, 0
	s_movk_i32 s5, 0x171
	s_cselect_b32 s5, s5, 0x170
	s_mul_i32 s1, s1, s5
	s_add_i32 s1, s1, s4
	s_mul_hi_i32 s4, s1, 0xb21642c9
	s_add_i32 s4, s4, s1
	s_lshr_b32 s5, s4, 31
	s_ashr_i32 s4, s4, 7
	s_add_i32 s4, s4, s5
	s_lshl_b32 s5, s4, 3
	s_mulk_i32 s4, 0xb8
	s_sub_i32 s1, s1, s4
	s_sext_i32_i16 s4, s1
	s_bfe_u32 s4, s4, 0x3001c
	s_add_i32 s4, s1, s4
	s_sext_i32_i16 s6, s4
	s_and_b32 s4, s4, 0xfff8
	s_sub_i32 s1, s1, s4
	s_sext_i32_i16 s1, s1
	s_add_i32 s33, s5, s1
	s_ashr_i32 s10, s6, 3
	s_and_b32 s32, s80, 7
	s_mul_i32 s32, s32, 3
	s_add_i32 s10, s10, s32
	s_sub_i32 s1, s10, 23
	s_cmp_ge_i32 s10, 23
	s_cselect_b32 s10, s1, s10
